# P8 hid stores widened to one plain 16-byte store per row per lane via v_permlane16_swap (no write-through on this stream)
# speedup vs baseline: 1.0090x; 1.0090x over previous
.Lp8_nonext:
	v_lshl_add_u32 v214, s8, 8, v146
	v_lshl_or_b32 v215, s0, 7, v148
	v_mul_u32_u24_e32 v154, 0x1600, v214
	v_lshl_add_u32 v154, v215, 1, v154
	v_bfe_u32 v216, v254, 4, 1
	v_mul_u32_u24_e32 v216, 0x78, v216
	v_add_u32_e32 v154, v154, v216
	v_add_u32_e32 v155, 0x16000, v154
	v_add_u32_e32 v156, 0x2c000, v154
	v_add_u32_e32 v157, 0x42000, v154
	v_add_u32_e32 v158, 0xb0000, v154
	v_add_u32_e32 v159, 0xc6000, v154
	v_add_u32_e32 v160, 0xdc000, v154
	v_add_u32_e32 v161, 0xf2000, v154
	s_waitcnt lgkmcnt(0)
	v_add_f32_e32 v174, v174, v175
	v_add_f32_e32 v178, v178, v179
	v_add_f32_e32 v182, v182, v183
	v_add_f32_e32 v186, v186, v187
	v_add_f32_e32 v190, v190, v191
	v_add_f32_e32 v194, v194, v195
	v_add_f32_e32 v198, v198, v199
	v_add_f32_e32 v202, v202, v203
	v_add_f32_e32 v174, v174, v176
	v_add_f32_e32 v178, v178, v180
	v_add_f32_e32 v182, v182, v184
	v_add_f32_e32 v186, v186, v188
	v_add_f32_e32 v190, v190, v192
	v_add_f32_e32 v194, v194, v196
	v_add_f32_e32 v198, v198, v200
	v_add_f32_e32 v202, v202, v204
	v_add_f32_e32 v174, v174, v177
	v_add_f32_e32 v178, v178, v181
	v_add_f32_e32 v182, v182, v185
	v_add_f32_e32 v186, v186, v189
	v_add_f32_e32 v190, v190, v193
	v_add_f32_e32 v194, v194, v197
	v_add_f32_e32 v198, v198, v201
	v_add_f32_e32 v202, v202, v205
	v_fmamk_f32 v174, v174, 0x3a800000, v152
	v_fmamk_f32 v178, v178, 0x3a800000, v152
	v_fmamk_f32 v182, v182, 0x3a800000, v152
	v_fmamk_f32 v186, v186, 0x3a800000, v152
	v_fmamk_f32 v190, v190, 0x3a800000, v152
	v_fmamk_f32 v194, v194, 0x3a800000, v152
	v_fmamk_f32 v198, v198, 0x3a800000, v152
	v_fmamk_f32 v202, v202, 0x3a800000, v152
	v_mul_f32_e32 v175, 0x4b800000, v174
	v_mul_f32_e32 v179, 0x4b800000, v178
	v_mul_f32_e32 v183, 0x4b800000, v182
	v_mul_f32_e32 v187, 0x4b800000, v186
	v_mul_f32_e32 v191, 0x4b800000, v190
	v_mul_f32_e32 v195, 0x4b800000, v194
	v_mul_f32_e32 v199, 0x4b800000, v198
	v_mul_f32_e32 v203, 0x4b800000, v202
	v_cmp_gt_f32_e64 s[74:75], s58, v174
	v_cmp_gt_f32_e64 s[76:77], s58, v178
	v_cmp_gt_f32_e64 s[78:79], s58, v182
	v_cmp_gt_f32_e64 s[80:81], s58, v186
	v_cmp_gt_f32_e64 s[82:83], s58, v190
	v_cmp_gt_f32_e64 s[84:85], s58, v194
	v_cmp_gt_f32_e64 s[86:87], s58, v198
	v_cmp_gt_f32_e64 s[88:89], s58, v202
	v_cndmask_b32_e64 v174, v174, v175, s[74:75]
	v_cndmask_b32_e64 v178, v178, v179, s[76:77]
	v_cndmask_b32_e64 v182, v182, v183, s[78:79]
	v_cndmask_b32_e64 v186, v186, v187, s[80:81]
	v_cndmask_b32_e64 v190, v190, v191, s[82:83]
	v_cndmask_b32_e64 v194, v194, v195, s[84:85]
	v_cndmask_b32_e64 v198, v198, v199, s[86:87]
	v_cndmask_b32_e64 v202, v202, v203, s[88:89]
	v_rsq_f32_e32 v174, v174
	v_rsq_f32_e32 v178, v178
	v_rsq_f32_e32 v182, v182
	v_rsq_f32_e32 v186, v186
	v_rsq_f32_e32 v190, v190
	v_rsq_f32_e32 v194, v194
	v_rsq_f32_e32 v198, v198
	v_rsq_f32_e32 v202, v202
	v_mul_f32_e32 v175, 0x45800000, v174
	v_mul_f32_e32 v179, 0x45800000, v178
	v_mul_f32_e32 v183, 0x45800000, v182
	v_mul_f32_e32 v187, 0x45800000, v186
	v_mul_f32_e32 v191, 0x45800000, v190
	v_mul_f32_e32 v195, 0x45800000, v194
	v_mul_f32_e32 v199, 0x45800000, v198
	v_mul_f32_e32 v203, 0x45800000, v202
	v_cndmask_b32_e64 v206, v174, v175, s[74:75]
	v_cndmask_b32_e64 v207, v178, v179, s[76:77]
	v_cndmask_b32_e64 v208, v182, v183, s[78:79]
	v_cndmask_b32_e64 v209, v186, v187, s[80:81]
	v_cndmask_b32_e64 v210, v190, v191, s[82:83]
	v_cndmask_b32_e64 v211, v194, v195, s[84:85]
	v_cndmask_b32_e64 v212, v198, v199, s[86:87]
	v_cndmask_b32_e64 v213, v202, v203, s[88:89]
	s_mov_b32 s90, 0xbfb8aa3b
	v_pk_mul_f32 v[120:121], v[120:121], v[206:207] op_sel_hi:[1,0]
	v_pk_mul_f32 v[122:123], v[122:123], v[206:207] op_sel_hi:[1,0]
	v_pk_mul_f32 v[116:117], v[116:117], v[206:207] op_sel_hi:[1,0]
	v_pk_mul_f32 v[118:119], v[118:119], v[206:207] op_sel_hi:[1,0]
	v_pk_mul_f32 v[124:125], v[124:125], v[206:207] op_sel_hi:[1,0]
	v_pk_mul_f32 v[126:127], v[126:127], v[206:207] op_sel_hi:[1,0]
	v_pk_mul_f32 v[112:113], v[112:113], v[206:207] op_sel_hi:[1,0]
	v_pk_mul_f32 v[114:115], v[114:115], v[206:207] op_sel_hi:[1,0]
	v_pk_mul_f32 v[174:175], v[120:121], s[90:91] op_sel_hi:[1,0]
	v_pk_mul_f32 v[176:177], v[122:123], s[90:91] op_sel_hi:[1,0]
	v_pk_mul_f32 v[178:179], v[116:117], s[90:91] op_sel_hi:[1,0]
	v_pk_mul_f32 v[180:181], v[118:119], s[90:91] op_sel_hi:[1,0]
	v_exp_f32_e32 v174, v174
	v_exp_f32_e32 v175, v175
	v_exp_f32_e32 v176, v176
	v_exp_f32_e32 v177, v177
	v_exp_f32_e32 v178, v178
	v_exp_f32_e32 v179, v179
	v_exp_f32_e32 v180, v180
	v_exp_f32_e32 v181, v181
	v_pk_add_f32 v[174:175], v[174:175], 1.0 op_sel_hi:[1,0]
	v_pk_add_f32 v[176:177], v[176:177], 1.0 op_sel_hi:[1,0]
	v_pk_add_f32 v[178:179], v[178:179], 1.0 op_sel_hi:[1,0]
	v_pk_add_f32 v[180:181], v[180:181], 1.0 op_sel_hi:[1,0]
	v_rcp_f32_e32 v174, v174
	v_rcp_f32_e32 v175, v175
	v_rcp_f32_e32 v176, v176
	v_rcp_f32_e32 v177, v177
	v_rcp_f32_e32 v178, v178
	v_rcp_f32_e32 v179, v179
	v_rcp_f32_e32 v180, v180
	v_rcp_f32_e32 v181, v181
	v_pk_mul_f32 v[120:121], v[120:121], v[174:175]
	v_pk_mul_f32 v[122:123], v[122:123], v[176:177]
	v_pk_mul_f32 v[116:117], v[116:117], v[178:179]
	v_pk_mul_f32 v[118:119], v[118:119], v[180:181]
	v_pk_mul_f32 v[120:121], v[124:125], v[120:121]
	v_pk_mul_f32 v[122:123], v[126:127], v[122:123]
	v_pk_mul_f32 v[116:117], v[112:113], v[116:117]
	v_pk_mul_f32 v[118:119], v[114:115], v[118:119]
	v_cvt_pk_bf16_f32 v120, v120, v121
	v_cvt_pk_bf16_f32 v121, v122, v123
	v_cvt_pk_bf16_f32 v122, v116, v117
	v_cvt_pk_bf16_f32 v123, v118, v119
	s_nop 1
	v_permlane16_swap_b32 v120, v122
	v_permlane16_swap_b32 v121, v123
	global_store_dwordx4 v154, v[120:123], s[34:35]
	v_pk_mul_f32 v[108:109], v[108:109], v[206:207] op_sel:[0,1] op_sel_hi:[1,1]
	v_pk_mul_f32 v[110:111], v[110:111], v[206:207] op_sel:[0,1] op_sel_hi:[1,1]
	v_pk_mul_f32 v[100:101], v[100:101], v[206:207] op_sel:[0,1] op_sel_hi:[1,1]
	v_pk_mul_f32 v[102:103], v[102:103], v[206:207] op_sel:[0,1] op_sel_hi:[1,1]
	v_pk_mul_f32 v[104:105], v[104:105], v[206:207] op_sel:[0,1] op_sel_hi:[1,1]
	v_pk_mul_f32 v[106:107], v[106:107], v[206:207] op_sel:[0,1] op_sel_hi:[1,1]
	v_pk_mul_f32 v[96:97], v[96:97], v[206:207] op_sel:[0,1] op_sel_hi:[1,1]
	v_pk_mul_f32 v[98:99], v[98:99], v[206:207] op_sel:[0,1] op_sel_hi:[1,1]
	v_pk_mul_f32 v[174:175], v[108:109], s[90:91] op_sel_hi:[1,0]
	v_pk_mul_f32 v[176:177], v[110:111], s[90:91] op_sel_hi:[1,0]
	v_pk_mul_f32 v[178:179], v[100:101], s[90:91] op_sel_hi:[1,0]
	v_pk_mul_f32 v[180:181], v[102:103], s[90:91] op_sel_hi:[1,0]
	v_exp_f32_e32 v174, v174
	v_exp_f32_e32 v175, v175
	v_exp_f32_e32 v176, v176
	v_exp_f32_e32 v177, v177
	v_exp_f32_e32 v178, v178
	v_exp_f32_e32 v179, v179
	v_exp_f32_e32 v180, v180
	v_exp_f32_e32 v181, v181
	v_pk_add_f32 v[174:175], v[174:175], 1.0 op_sel_hi:[1,0]
	v_pk_add_f32 v[176:177], v[176:177], 1.0 op_sel_hi:[1,0]
	v_pk_add_f32 v[178:179], v[178:179], 1.0 op_sel_hi:[1,0]
	v_pk_add_f32 v[180:181], v[180:181], 1.0 op_sel_hi:[1,0]
	v_rcp_f32_e32 v174, v174
	v_rcp_f32_e32 v175, v175
	v_rcp_f32_e32 v176, v176
	v_rcp_f32_e32 v177, v177
	v_rcp_f32_e32 v178, v178
	v_rcp_f32_e32 v179, v179
	v_rcp_f32_e32 v180, v180
	v_rcp_f32_e32 v181, v181
	v_pk_mul_f32 v[108:109], v[108:109], v[174:175]
	v_pk_mul_f32 v[110:111], v[110:111], v[176:177]
	v_pk_mul_f32 v[100:101], v[100:101], v[178:179]
	v_pk_mul_f32 v[102:103], v[102:103], v[180:181]
	v_pk_mul_f32 v[108:109], v[104:105], v[108:109]
	v_pk_mul_f32 v[110:111], v[106:107], v[110:111]
	v_pk_mul_f32 v[100:101], v[96:97], v[100:101]
	v_pk_mul_f32 v[102:103], v[98:99], v[102:103]
	v_cvt_pk_bf16_f32 v108, v108, v109
	v_cvt_pk_bf16_f32 v109, v110, v111
	v_cvt_pk_bf16_f32 v110, v100, v101
	v_cvt_pk_bf16_f32 v111, v102, v103
	s_nop 1
	v_permlane16_swap_b32 v108, v110
	v_permlane16_swap_b32 v109, v111
	global_store_dwordx4 v155, v[108:111], s[34:35]
	v_pk_mul_f32 v[92:93], v[92:93], v[208:209] op_sel_hi:[1,0]
	v_pk_mul_f32 v[94:95], v[94:95], v[208:209] op_sel_hi:[1,0]
	v_pk_mul_f32 v[84:85], v[84:85], v[208:209] op_sel_hi:[1,0]
	v_pk_mul_f32 v[86:87], v[86:87], v[208:209] op_sel_hi:[1,0]
	v_pk_mul_f32 v[88:89], v[88:89], v[208:209] op_sel_hi:[1,0]
	v_pk_mul_f32 v[90:91], v[90:91], v[208:209] op_sel_hi:[1,0]
	v_pk_mul_f32 v[80:81], v[80:81], v[208:209] op_sel_hi:[1,0]
	v_pk_mul_f32 v[82:83], v[82:83], v[208:209] op_sel_hi:[1,0]
	v_pk_mul_f32 v[174:175], v[92:93], s[90:91] op_sel_hi:[1,0]
	v_pk_mul_f32 v[176:177], v[94:95], s[90:91] op_sel_hi:[1,0]
	v_pk_mul_f32 v[178:179], v[84:85], s[90:91] op_sel_hi:[1,0]
	v_pk_mul_f32 v[180:181], v[86:87], s[90:91] op_sel_hi:[1,0]
	v_exp_f32_e32 v174, v174
	v_exp_f32_e32 v175, v175
	v_exp_f32_e32 v176, v176
	v_exp_f32_e32 v177, v177
	v_exp_f32_e32 v178, v178
	v_exp_f32_e32 v179, v179
	v_exp_f32_e32 v180, v180
	v_exp_f32_e32 v181, v181
	v_pk_add_f32 v[174:175], v[174:175], 1.0 op_sel_hi:[1,0]
	v_pk_add_f32 v[176:177], v[176:177], 1.0 op_sel_hi:[1,0]
	v_pk_add_f32 v[178:179], v[178:179], 1.0 op_sel_hi:[1,0]
	v_pk_add_f32 v[180:181], v[180:181], 1.0 op_sel_hi:[1,0]
	v_rcp_f32_e32 v174, v174
	v_rcp_f32_e32 v175, v175
	v_rcp_f32_e32 v176, v176
	v_rcp_f32_e32 v177, v177
	v_rcp_f32_e32 v178, v178
	v_rcp_f32_e32 v179, v179
	v_rcp_f32_e32 v180, v180
	v_rcp_f32_e32 v181, v181
	v_pk_mul_f32 v[92:93], v[92:93], v[174:175]
	v_pk_mul_f32 v[94:95], v[94:95], v[176:177]
	v_pk_mul_f32 v[84:85], v[84:85], v[178:179]
	v_pk_mul_f32 v[86:87], v[86:87], v[180:181]
	v_pk_mul_f32 v[92:93], v[88:89], v[92:93]
	v_pk_mul_f32 v[94:95], v[90:91], v[94:95]
	v_pk_mul_f32 v[84:85], v[80:81], v[84:85]
	v_pk_mul_f32 v[86:87], v[82:83], v[86:87]
	v_cvt_pk_bf16_f32 v92, v92, v93
	v_cvt_pk_bf16_f32 v93, v94, v95
	v_cvt_pk_bf16_f32 v94, v84, v85
	v_cvt_pk_bf16_f32 v95, v86, v87
	s_nop 1
	v_permlane16_swap_b32 v92, v94
	v_permlane16_swap_b32 v93, v95
	global_store_dwordx4 v156, v[92:95], s[34:35]
	v_pk_mul_f32 v[76:77], v[76:77], v[208:209] op_sel:[0,1] op_sel_hi:[1,1]
	v_pk_mul_f32 v[78:79], v[78:79], v[208:209] op_sel:[0,1] op_sel_hi:[1,1]
	v_pk_mul_f32 v[68:69], v[68:69], v[208:209] op_sel:[0,1] op_sel_hi:[1,1]
	v_pk_mul_f32 v[70:71], v[70:71], v[208:209] op_sel:[0,1] op_sel_hi:[1,1]
	v_pk_mul_f32 v[72:73], v[72:73], v[208:209] op_sel:[0,1] op_sel_hi:[1,1]
	v_pk_mul_f32 v[74:75], v[74:75], v[208:209] op_sel:[0,1] op_sel_hi:[1,1]
	v_pk_mul_f32 v[64:65], v[64:65], v[208:209] op_sel:[0,1] op_sel_hi:[1,1]
	v_pk_mul_f32 v[66:67], v[66:67], v[208:209] op_sel:[0,1] op_sel_hi:[1,1]
	v_pk_mul_f32 v[174:175], v[76:77], s[90:91] op_sel_hi:[1,0]
	v_pk_mul_f32 v[176:177], v[78:79], s[90:91] op_sel_hi:[1,0]
	v_pk_mul_f32 v[178:179], v[68:69], s[90:91] op_sel_hi:[1,0]
	v_pk_mul_f32 v[180:181], v[70:71], s[90:91] op_sel_hi:[1,0]
	v_exp_f32_e32 v174, v174
	v_exp_f32_e32 v175, v175
	v_exp_f32_e32 v176, v176
	v_exp_f32_e32 v177, v177
	v_exp_f32_e32 v178, v178
	v_exp_f32_e32 v179, v179
	v_exp_f32_e32 v180, v180
	v_exp_f32_e32 v181, v181
	v_pk_add_f32 v[174:175], v[174:175], 1.0 op_sel_hi:[1,0]
	v_pk_add_f32 v[176:177], v[176:177], 1.0 op_sel_hi:[1,0]
	v_pk_add_f32 v[178:179], v[178:179], 1.0 op_sel_hi:[1,0]
	v_pk_add_f32 v[180:181], v[180:181], 1.0 op_sel_hi:[1,0]
	v_rcp_f32_e32 v174, v174
	v_rcp_f32_e32 v175, v175
	v_rcp_f32_e32 v176, v176
	v_rcp_f32_e32 v177, v177
	v_rcp_f32_e32 v178, v178
	v_rcp_f32_e32 v179, v179
	v_rcp_f32_e32 v180, v180
	v_rcp_f32_e32 v181, v181
	v_pk_mul_f32 v[76:77], v[76:77], v[174:175]
	v_pk_mul_f32 v[78:79], v[78:79], v[176:177]
	v_pk_mul_f32 v[68:69], v[68:69], v[178:179]
	v_pk_mul_f32 v[70:71], v[70:71], v[180:181]
	v_pk_mul_f32 v[76:77], v[72:73], v[76:77]
	v_pk_mul_f32 v[78:79], v[74:75], v[78:79]
	v_pk_mul_f32 v[68:69], v[64:65], v[68:69]
	v_pk_mul_f32 v[70:71], v[66:67], v[70:71]
	v_cvt_pk_bf16_f32 v76, v76, v77
	v_cvt_pk_bf16_f32 v77, v78, v79
	v_cvt_pk_bf16_f32 v78, v68, v69
	v_cvt_pk_bf16_f32 v79, v70, v71
	s_nop 1
	v_permlane16_swap_b32 v76, v78
	v_permlane16_swap_b32 v77, v79
	global_store_dwordx4 v157, v[76:79], s[34:35]
	v_pk_mul_f32 v[60:61], v[60:61], v[210:211] op_sel_hi:[1,0]
	v_pk_mul_f32 v[62:63], v[62:63], v[210:211] op_sel_hi:[1,0]
	v_pk_mul_f32 v[52:53], v[52:53], v[210:211] op_sel_hi:[1,0]
	v_pk_mul_f32 v[54:55], v[54:55], v[210:211] op_sel_hi:[1,0]
	v_pk_mul_f32 v[56:57], v[56:57], v[210:211] op_sel_hi:[1,0]
	v_pk_mul_f32 v[58:59], v[58:59], v[210:211] op_sel_hi:[1,0]
	v_pk_mul_f32 v[48:49], v[48:49], v[210:211] op_sel_hi:[1,0]
	v_pk_mul_f32 v[50:51], v[50:51], v[210:211] op_sel_hi:[1,0]
	v_pk_mul_f32 v[174:175], v[60:61], s[90:91] op_sel_hi:[1,0]
	v_pk_mul_f32 v[176:177], v[62:63], s[90:91] op_sel_hi:[1,0]
	v_pk_mul_f32 v[178:179], v[52:53], s[90:91] op_sel_hi:[1,0]
	v_pk_mul_f32 v[180:181], v[54:55], s[90:91] op_sel_hi:[1,0]
	v_exp_f32_e32 v174, v174
	v_exp_f32_e32 v175, v175
	v_exp_f32_e32 v176, v176
	v_exp_f32_e32 v177, v177
	v_exp_f32_e32 v178, v178
	v_exp_f32_e32 v179, v179
	v_exp_f32_e32 v180, v180
	v_exp_f32_e32 v181, v181
	v_pk_add_f32 v[174:175], v[174:175], 1.0 op_sel_hi:[1,0]
	v_pk_add_f32 v[176:177], v[176:177], 1.0 op_sel_hi:[1,0]
	v_pk_add_f32 v[178:179], v[178:179], 1.0 op_sel_hi:[1,0]
	v_pk_add_f32 v[180:181], v[180:181], 1.0 op_sel_hi:[1,0]
	v_rcp_f32_e32 v174, v174
	v_rcp_f32_e32 v175, v175
	v_rcp_f32_e32 v176, v176
	v_rcp_f32_e32 v177, v177
	v_rcp_f32_e32 v178, v178
	v_rcp_f32_e32 v179, v179
	v_rcp_f32_e32 v180, v180
	v_rcp_f32_e32 v181, v181
	v_pk_mul_f32 v[60:61], v[60:61], v[174:175]
	v_pk_mul_f32 v[62:63], v[62:63], v[176:177]
	v_pk_mul_f32 v[52:53], v[52:53], v[178:179]
	v_pk_mul_f32 v[54:55], v[54:55], v[180:181]
	v_pk_mul_f32 v[60:61], v[56:57], v[60:61]
	v_pk_mul_f32 v[62:63], v[58:59], v[62:63]
	v_pk_mul_f32 v[52:53], v[48:49], v[52:53]
	v_pk_mul_f32 v[54:55], v[50:51], v[54:55]
	v_cvt_pk_bf16_f32 v60, v60, v61
	v_cvt_pk_bf16_f32 v61, v62, v63
	v_cvt_pk_bf16_f32 v62, v52, v53
	v_cvt_pk_bf16_f32 v63, v54, v55
	s_nop 1
	v_permlane16_swap_b32 v60, v62
	v_permlane16_swap_b32 v61, v63
	global_store_dwordx4 v158, v[60:63], s[34:35]
	v_pk_mul_f32 v[44:45], v[44:45], v[210:211] op_sel:[0,1] op_sel_hi:[1,1]
	v_pk_mul_f32 v[46:47], v[46:47], v[210:211] op_sel:[0,1] op_sel_hi:[1,1]
	v_pk_mul_f32 v[36:37], v[36:37], v[210:211] op_sel:[0,1] op_sel_hi:[1,1]
	v_pk_mul_f32 v[38:39], v[38:39], v[210:211] op_sel:[0,1] op_sel_hi:[1,1]
	v_pk_mul_f32 v[40:41], v[40:41], v[210:211] op_sel:[0,1] op_sel_hi:[1,1]
	v_pk_mul_f32 v[42:43], v[42:43], v[210:211] op_sel:[0,1] op_sel_hi:[1,1]
	v_pk_mul_f32 v[32:33], v[32:33], v[210:211] op_sel:[0,1] op_sel_hi:[1,1]
	v_pk_mul_f32 v[34:35], v[34:35], v[210:211] op_sel:[0,1] op_sel_hi:[1,1]
	v_pk_mul_f32 v[174:175], v[44:45], s[90:91] op_sel_hi:[1,0]
	v_pk_mul_f32 v[176:177], v[46:47], s[90:91] op_sel_hi:[1,0]
	v_pk_mul_f32 v[178:179], v[36:37], s[90:91] op_sel_hi:[1,0]
	v_pk_mul_f32 v[180:181], v[38:39], s[90:91] op_sel_hi:[1,0]
	v_exp_f32_e32 v174, v174
	v_exp_f32_e32 v175, v175
	v_exp_f32_e32 v176, v176
	v_exp_f32_e32 v177, v177
	v_exp_f32_e32 v178, v178
	v_exp_f32_e32 v179, v179
	v_exp_f32_e32 v180, v180
	v_exp_f32_e32 v181, v181
	v_pk_add_f32 v[174:175], v[174:175], 1.0 op_sel_hi:[1,0]
	v_pk_add_f32 v[176:177], v[176:177], 1.0 op_sel_hi:[1,0]
	v_pk_add_f32 v[178:179], v[178:179], 1.0 op_sel_hi:[1,0]
	v_pk_add_f32 v[180:181], v[180:181], 1.0 op_sel_hi:[1,0]
	v_rcp_f32_e32 v174, v174
	v_rcp_f32_e32 v175, v175
	v_rcp_f32_e32 v176, v176
	v_rcp_f32_e32 v177, v177
	v_rcp_f32_e32 v178, v178
	v_rcp_f32_e32 v179, v179
	v_rcp_f32_e32 v180, v180
	v_rcp_f32_e32 v181, v181
	v_pk_mul_f32 v[44:45], v[44:45], v[174:175]
	v_pk_mul_f32 v[46:47], v[46:47], v[176:177]
	v_pk_mul_f32 v[36:37], v[36:37], v[178:179]
	v_pk_mul_f32 v[38:39], v[38:39], v[180:181]
	v_pk_mul_f32 v[44:45], v[40:41], v[44:45]
	v_pk_mul_f32 v[46:47], v[42:43], v[46:47]
	v_pk_mul_f32 v[36:37], v[32:33], v[36:37]
	v_pk_mul_f32 v[38:39], v[34:35], v[38:39]
	v_cvt_pk_bf16_f32 v44, v44, v45
	v_cvt_pk_bf16_f32 v45, v46, v47
	v_cvt_pk_bf16_f32 v46, v36, v37
	v_cvt_pk_bf16_f32 v47, v38, v39
	s_nop 1
	v_permlane16_swap_b32 v44, v46
	v_permlane16_swap_b32 v45, v47
	global_store_dwordx4 v159, v[44:47], s[34:35]
	v_pk_mul_f32 v[28:29], v[28:29], v[212:213] op_sel_hi:[1,0]
	v_pk_mul_f32 v[30:31], v[30:31], v[212:213] op_sel_hi:[1,0]
	v_pk_mul_f32 v[20:21], v[20:21], v[212:213] op_sel_hi:[1,0]
	v_pk_mul_f32 v[22:23], v[22:23], v[212:213] op_sel_hi:[1,0]
	v_pk_mul_f32 v[24:25], v[24:25], v[212:213] op_sel_hi:[1,0]
	v_pk_mul_f32 v[26:27], v[26:27], v[212:213] op_sel_hi:[1,0]
	v_pk_mul_f32 v[16:17], v[16:17], v[212:213] op_sel_hi:[1,0]
	v_pk_mul_f32 v[18:19], v[18:19], v[212:213] op_sel_hi:[1,0]
	v_pk_mul_f32 v[174:175], v[28:29], s[90:91] op_sel_hi:[1,0]
	v_pk_mul_f32 v[176:177], v[30:31], s[90:91] op_sel_hi:[1,0]
	v_pk_mul_f32 v[178:179], v[20:21], s[90:91] op_sel_hi:[1,0]
	v_pk_mul_f32 v[180:181], v[22:23], s[90:91] op_sel_hi:[1,0]
	v_exp_f32_e32 v174, v174
	v_exp_f32_e32 v175, v175
	v_exp_f32_e32 v176, v176
	v_exp_f32_e32 v177, v177
	v_exp_f32_e32 v178, v178
	v_exp_f32_e32 v179, v179
	v_exp_f32_e32 v180, v180
	v_exp_f32_e32 v181, v181
	v_pk_add_f32 v[174:175], v[174:175], 1.0 op_sel_hi:[1,0]
	v_pk_add_f32 v[176:177], v[176:177], 1.0 op_sel_hi:[1,0]
	v_pk_add_f32 v[178:179], v[178:179], 1.0 op_sel_hi:[1,0]
	v_pk_add_f32 v[180:181], v[180:181], 1.0 op_sel_hi:[1,0]
	v_rcp_f32_e32 v174, v174
	v_rcp_f32_e32 v175, v175
	v_rcp_f32_e32 v176, v176
	v_rcp_f32_e32 v177, v177
	v_rcp_f32_e32 v178, v178
	v_rcp_f32_e32 v179, v179
	v_rcp_f32_e32 v180, v180
	v_rcp_f32_e32 v181, v181
	v_pk_mul_f32 v[28:29], v[28:29], v[174:175]
	v_pk_mul_f32 v[30:31], v[30:31], v[176:177]
	v_pk_mul_f32 v[20:21], v[20:21], v[178:179]
	v_pk_mul_f32 v[22:23], v[22:23], v[180:181]
	v_pk_mul_f32 v[28:29], v[24:25], v[28:29]
	v_pk_mul_f32 v[30:31], v[26:27], v[30:31]
	v_pk_mul_f32 v[20:21], v[16:17], v[20:21]
	v_pk_mul_f32 v[22:23], v[18:19], v[22:23]
	v_cvt_pk_bf16_f32 v28, v28, v29
	v_cvt_pk_bf16_f32 v29, v30, v31
	v_cvt_pk_bf16_f32 v30, v20, v21
	v_cvt_pk_bf16_f32 v31, v22, v23
	s_nop 1
	v_permlane16_swap_b32 v28, v30
	v_permlane16_swap_b32 v29, v31
	global_store_dwordx4 v160, v[28:31], s[34:35]
	v_pk_mul_f32 v[12:13], v[12:13], v[212:213] op_sel:[0,1] op_sel_hi:[1,1]
	v_pk_mul_f32 v[14:15], v[14:15], v[212:213] op_sel:[0,1] op_sel_hi:[1,1]
	v_pk_mul_f32 v[4:5], v[4:5], v[212:213] op_sel:[0,1] op_sel_hi:[1,1]
	v_pk_mul_f32 v[6:7], v[6:7], v[212:213] op_sel:[0,1] op_sel_hi:[1,1]
	v_pk_mul_f32 v[8:9], v[8:9], v[212:213] op_sel:[0,1] op_sel_hi:[1,1]
	v_pk_mul_f32 v[10:11], v[10:11], v[212:213] op_sel:[0,1] op_sel_hi:[1,1]
	v_pk_mul_f32 v[0:1], v[0:1], v[212:213] op_sel:[0,1] op_sel_hi:[1,1]
	v_pk_mul_f32 v[2:3], v[2:3], v[212:213] op_sel:[0,1] op_sel_hi:[1,1]
	v_pk_mul_f32 v[174:175], v[12:13], s[90:91] op_sel_hi:[1,0]
	v_pk_mul_f32 v[176:177], v[14:15], s[90:91] op_sel_hi:[1,0]
	v_pk_mul_f32 v[178:179], v[4:5], s[90:91] op_sel_hi:[1,0]
	v_pk_mul_f32 v[180:181], v[6:7], s[90:91] op_sel_hi:[1,0]
	v_exp_f32_e32 v174, v174
	v_exp_f32_e32 v175, v175
	v_exp_f32_e32 v176, v176
	v_exp_f32_e32 v177, v177
	v_exp_f32_e32 v178, v178
	v_exp_f32_e32 v179, v179
	v_exp_f32_e32 v180, v180
	v_exp_f32_e32 v181, v181
	v_pk_add_f32 v[174:175], v[174:175], 1.0 op_sel_hi:[1,0]
	v_pk_add_f32 v[176:177], v[176:177], 1.0 op_sel_hi:[1,0]
	v_pk_add_f32 v[178:179], v[178:179], 1.0 op_sel_hi:[1,0]
	v_pk_add_f32 v[180:181], v[180:181], 1.0 op_sel_hi:[1,0]
	v_rcp_f32_e32 v174, v174
	v_rcp_f32_e32 v175, v175
	v_rcp_f32_e32 v176, v176
	v_rcp_f32_e32 v177, v177
	v_rcp_f32_e32 v178, v178
	v_rcp_f32_e32 v179, v179
	v_rcp_f32_e32 v180, v180
	v_rcp_f32_e32 v181, v181
	v_pk_mul_f32 v[12:13], v[12:13], v[174:175]
	v_pk_mul_f32 v[14:15], v[14:15], v[176:177]
	v_pk_mul_f32 v[4:5], v[4:5], v[178:179]
	v_pk_mul_f32 v[6:7], v[6:7], v[180:181]
	v_pk_mul_f32 v[12:13], v[8:9], v[12:13]
	v_pk_mul_f32 v[14:15], v[10:11], v[14:15]
	v_pk_mul_f32 v[4:5], v[0:1], v[4:5]
	v_pk_mul_f32 v[6:7], v[2:3], v[6:7]
	v_cvt_pk_bf16_f32 v12, v12, v13
	v_cvt_pk_bf16_f32 v13, v14, v15
	v_cvt_pk_bf16_f32 v14, v4, v5
	v_cvt_pk_bf16_f32 v15, v6, v7
	s_nop 1
	v_permlane16_swap_b32 v12, v14
	v_permlane16_swap_b32 v13, v15
	global_store_dwordx4 v161, v[12:15], s[34:35]
	s_andn2_b64 vcc, exec, s[6:7]
	s_mov_b64 s[6:7], -1
	s_cbranch_vccnz .LBB0_543
	s_andn2_b64 vcc, exec, s[14:15]
	s_cbranch_vccnz .LBB0_542
	s_barrier
	s_branch .LBB0_542
